# first grid barrier: group-size / XCC-count computation and its two LDS words produced before the workgroup barrier from the speculative census (overlapping the store drain); thread 0 then takes the in
# baseline (speedup 1.0000x reference)
; __device__ __forceinline__ unsigned xb_ld(unsigned* p)              { return __hip_atomic_load(p, __ATOMIC_RELAXED, __HIP_MEMORY_SCOPE_AGENT); }
; __device__ __forceinline__ void xcd_barrier_complete(unsigned* bar, unsigned x, unsigned& nloc, unsigned& nx) {
;     const unsigned G = gridDim.x * gridDim.y * gridDim.z;
;     unsigned sum, cnt, mine, sp = 0u;
;     for (;;) {
;         sum = 0u; cnt = 0u; mine = 0u;
; #pragma unroll
;         for (unsigned j = 0; j < 16; ++j) { const unsigned c = xb_ld(&bar[XB_XCNT(j)]); sum += c; cnt += (c > 0u) ? 1u : 0u; mine = (j == x) ? c : mine; }
;         if (sum == G) break;
;         __builtin_amdgcn_s_sleep(1);
;         if ((++sp & 255u) == 0u) { if (xb_ld(&bar[XB_TMO])) break; if (sp > XB_SPIN_CAP) { atomicAdd(&bar[XB_TMO], 1u); break; } }
;     }
;     nloc = mine > 0u ? mine : 1u; nx = cnt > 0u ? cnt : 1u;
; }
; __device__ __forceinline__ void xcd_barrier(const XcdBarrier& b) {
;     asm volatile("s_waitcnt vmcnt(0)" ::: "memory");
;     __syncthreads();
;     if (threadIdx.x == 0) {
;         unsigned* bar = b.bar;
;         __builtin_amdgcn_s_waitcnt(0);
;         unsigned nloc = b.st[0], nx = b.st[1];
;         if (nloc == 0u) { xcd_barrier_complete(bar, b.x, nloc, nx); b.st[0] = nloc; b.st[1] = nx; }
.LBB0_70:
	s_waitcnt lgkmcnt(0)
	s_mul_i32 s4, s58, s99
	s_mul_i32 s4, s4, s59
	v_add_u32_e32 v17, v232, v233
	v_add_u32_e32 v17, v17, v234
	v_add_u32_e32 v17, v17, v235
	v_add_u32_e32 v17, v17, v236
	v_add_u32_e32 v17, v17, v237
	v_add_u32_e32 v17, v17, v238
	v_add_u32_e32 v17, v17, v239
	v_add_u32_e32 v17, v17, v240
	v_add_u32_e32 v17, v17, v241
	v_add_u32_e32 v17, v17, v242
	v_add_u32_e32 v17, v17, v243
	v_add_u32_e32 v17, v17, v244
	v_add_u32_e32 v17, v17, v245
	v_add_u32_e32 v17, v17, v246
	v_add_u32_e32 v17, v17, v247
	v_cmp_ne_u32_e32 vcc, s4, v17
	s_cbranch_vccnz .Lcen_skip
	v_mov_b32_e32 v15, v232
	v_mov_b32_e32 v0, v233
	v_mov_b32_e32 v1, v234
	v_mov_b32_e32 v2, v235
	v_mov_b32_e32 v3, v236
	v_mov_b32_e32 v4, v237
	v_mov_b32_e32 v5, v238
	v_mov_b32_e32 v6, v239
	v_mov_b32_e32 v7, v240
	v_mov_b32_e32 v8, v241
	v_mov_b32_e32 v9, v242
	v_mov_b32_e32 v10, v243
	v_mov_b32_e32 v11, v244
	v_mov_b32_e32 v12, v245
	v_mov_b32_e32 v13, v246
	v_mov_b32_e32 v14, v247
	v_readlane_b32 s4, v253, 22
	s_cmp_eq_u32 s4, 0
	s_cselect_b64 vcc, -1, 0
	s_cmp_eq_u32 s4, 1
	v_cndmask_b32_e32 v16, 0, v15, vcc
	s_cselect_b64 vcc, -1, 0
	s_cmp_eq_u32 s4, 2
	v_cndmask_b32_e32 v16, v16, v0, vcc
	s_cselect_b64 vcc, -1, 0
	s_cmp_eq_u32 s4, 3
	v_cndmask_b32_e32 v16, v16, v1, vcc
	s_cselect_b64 vcc, -1, 0
	s_cmp_eq_u32 s4, 4
	v_cndmask_b32_e32 v16, v16, v2, vcc
	s_cselect_b64 vcc, -1, 0
	s_cmp_eq_u32 s4, 5
	v_cndmask_b32_e32 v16, v16, v3, vcc
	s_cselect_b64 vcc, -1, 0
	s_cmp_eq_u32 s4, 6
	v_cndmask_b32_e32 v16, v16, v4, vcc
	s_cselect_b64 vcc, -1, 0
	s_cmp_eq_u32 s4, 7
	v_cndmask_b32_e32 v16, v16, v5, vcc
	s_cselect_b64 vcc, -1, 0
	s_cmp_eq_u32 s4, 8
	v_cndmask_b32_e32 v16, v16, v6, vcc
	s_cselect_b64 vcc, -1, 0
	s_cmp_eq_u32 s4, 9
	v_cndmask_b32_e32 v16, v16, v7, vcc
	s_cselect_b64 vcc, -1, 0
	s_cmp_eq_u32 s4, 10
	v_cndmask_b32_e32 v16, v16, v8, vcc
	s_cselect_b64 vcc, -1, 0
	s_cmp_eq_u32 s4, 11
	v_cndmask_b32_e32 v16, v16, v9, vcc
	s_cselect_b64 vcc, -1, 0
	s_cmp_eq_u32 s4, 12
	v_cndmask_b32_e32 v16, v16, v10, vcc
	s_cselect_b64 vcc, -1, 0
	s_cmp_eq_u32 s4, 13
	v_cndmask_b32_e32 v16, v16, v11, vcc
	s_cselect_b64 vcc, -1, 0
	s_cmp_eq_u32 s4, 14
	v_cndmask_b32_e32 v16, v16, v12, vcc
	s_cselect_b64 vcc, -1, 0
	s_cmp_eq_u32 s4, 15
	v_cndmask_b32_e32 v16, v16, v13, vcc
	s_cselect_b64 vcc, -1, 0
	v_cndmask_b32_e32 v16, v16, v14, vcc
	v_cmp_ne_u32_e32 vcc, 0, v15
	s_add_i32 s4, 0, 0x20420
	s_nop 0
	v_cndmask_b32_e64 v15, 0, 1, vcc
	v_cmp_ne_u32_e32 vcc, 0, v0
	s_nop 1
	v_addc_co_u32_e32 v0, vcc, 0, v15, vcc
	v_cmp_ne_u32_e32 vcc, 0, v1
	s_nop 1
	v_cndmask_b32_e64 v1, 0, 1, vcc
	v_cmp_ne_u32_e32 vcc, 0, v2
	v_max_u32_e32 v2, 1, v16
	s_nop 0
	v_addc_co_u32_e32 v0, vcc, v0, v1, vcc
	v_cmp_ne_u32_e32 vcc, 0, v3
	s_nop 1
	v_cndmask_b32_e64 v1, 0, 1, vcc
	v_cmp_ne_u32_e32 vcc, 0, v4
	s_nop 1
	v_addc_co_u32_e32 v0, vcc, v0, v1, vcc
	v_cmp_ne_u32_e32 vcc, 0, v5
	s_nop 1
	v_cndmask_b32_e64 v1, 0, 1, vcc
	v_cmp_ne_u32_e32 vcc, 0, v6
	s_nop 1
	v_addc_co_u32_e32 v0, vcc, v0, v1, vcc
	v_cmp_ne_u32_e32 vcc, 0, v7
	s_nop 1
	v_cndmask_b32_e64 v1, 0, 1, vcc
	v_cmp_ne_u32_e32 vcc, 0, v8
	s_nop 1
	v_addc_co_u32_e32 v0, vcc, v0, v1, vcc
	v_cmp_ne_u32_e32 vcc, 0, v9
	s_nop 1
	v_cndmask_b32_e64 v1, 0, 1, vcc
	v_cmp_ne_u32_e32 vcc, 0, v10
	s_nop 1
	v_addc_co_u32_e32 v0, vcc, v0, v1, vcc
	v_cmp_ne_u32_e32 vcc, 0, v11
	s_nop 1
	v_cndmask_b32_e64 v1, 0, 1, vcc
	v_cmp_ne_u32_e32 vcc, 0, v12
	s_nop 1
	v_addc_co_u32_e32 v0, vcc, v0, v1, vcc
	v_cmp_ne_u32_e32 vcc, 0, v13
	s_nop 1
	v_cndmask_b32_e64 v1, 0, 1, vcc
	v_cmp_ne_u32_e32 vcc, 0, v14
	s_nop 1
	v_addc_co_u32_e32 v0, vcc, v0, v1, vcc
	v_mov_b32_e32 v1, s4
	s_add_i32 s4, 0, 0x20424
	v_max_u32_e32 v0, 1, v0
	ds_write_b32 v1, v2
	v_mov_b32_e32 v1, s4
	ds_write_b32 v1, v0
	s_waitcnt lgkmcnt(0)
